# v20 + P6 epilogue: ple_norm gains loaded once instead of after every y store pair, vmcnt re-derived
# speedup vs baseline: 1.0271x; 1.0271x over previous
.LBB0_762:
	ds_read_b128 v[130:133], v212
	ds_read_b128 v[134:137], v212 offset:1024
	ds_read_b128 v[138:141], v212 offset:2048
	ds_read_b128 v[142:145], v212 offset:3072
	ds_read_b128 v[146:149], v213
	ds_read_b128 v[150:153], v213 offset:1024
	ds_read_b128 v[154:157], v213 offset:2048
	ds_read_b128 v[158:161], v213 offset:3072
	s_add_u32 s30, s28, 0xfffc0080
	s_addc_u32 s31, s29, -1
	s_cmp_eq_u32 s49, 12
	s_cselect_b32 s35, s9, s31
	s_cselect_b32 s34, s33, s30
	s_cselect_b32 s31, s7, s48
	s_cselect_b32 s30, s46, s47
	v_lshl_add_u64 v[194:195], s[28:29], 0, v[170:171]
	s_add_i32 m0, s25, 0xc000
	ds_read_b128 v[178:181], v214
	ds_read_b128 v[182:185], v214 offset:1024
	ds_read_b128 v[216:219], v214 offset:2048
	ds_read_b128 v[220:223], v214 offset:3072
	ds_read_b128 v[224:227], v214 offset:4096
	ds_read_b128 v[228:231], v214 offset:5120
	ds_read_b128 v[232:235], v214 offset:6144
	ds_read_b128 v[236:239], v214 offset:7168
	global_load_lds_dwordx4 v[194:195], off
	v_lshl_add_u64 v[194:195], s[28:29], 0, v[172:173]
	s_add_i32 m0, s25, 0xe000
	s_nop 0
	global_load_lds_dwordx4 v[194:195], off
	s_waitcnt vmcnt(8)
	s_waitcnt lgkmcnt(0)
	s_barrier
	s_setprio 1
	s_waitcnt lgkmcnt(0)
	v_mfma_f32_16x16x32_bf16 v[126:129], v[130:133], v[178:181], v[126:129]
	v_mfma_f32_16x16x32_bf16 v[122:125], v[138:141], v[178:181], v[122:125]
	v_mfma_f32_16x16x32_bf16 v[110:113], v[130:133], v[216:219], v[110:113]
	v_mfma_f32_16x16x32_bf16 v[106:109], v[138:141], v[216:219], v[106:109]
	v_mfma_f32_16x16x32_bf16 v[94:97], v[130:133], v[224:227], v[94:97]
	v_mfma_f32_16x16x32_bf16 v[90:93], v[138:141], v[224:227], v[90:93]
	v_mfma_f32_16x16x32_bf16 v[78:81], v[130:133], v[232:235], v[78:81]
	v_mfma_f32_16x16x32_bf16 v[74:77], v[138:141], v[232:235], v[74:77]
	v_mfma_f32_16x16x32_bf16 v[126:129], v[134:137], v[182:185], v[126:129]
	v_mfma_f32_16x16x32_bf16 v[122:125], v[142:145], v[182:185], v[122:125]
	v_mfma_f32_16x16x32_bf16 v[110:113], v[134:137], v[220:223], v[110:113]
	v_mfma_f32_16x16x32_bf16 v[106:109], v[142:145], v[220:223], v[106:109]
	v_mfma_f32_16x16x32_bf16 v[94:97], v[134:137], v[228:231], v[94:97]
	v_mfma_f32_16x16x32_bf16 v[90:93], v[142:145], v[228:231], v[90:93]
	v_mfma_f32_16x16x32_bf16 v[78:81], v[134:137], v[236:239], v[78:81]
	v_mfma_f32_16x16x32_bf16 v[74:77], v[142:145], v[236:239], v[74:77]
	s_setprio 0
	s_setprio 1
	v_mfma_f32_16x16x32_bf16 v[118:121], v[146:149], v[178:181], v[118:121]
	v_mfma_f32_16x16x32_bf16 v[114:117], v[154:157], v[178:181], v[114:117]
	v_mfma_f32_16x16x32_bf16 v[102:105], v[146:149], v[216:219], v[102:105]
	v_mfma_f32_16x16x32_bf16 v[98:101], v[154:157], v[216:219], v[98:101]
	v_mfma_f32_16x16x32_bf16 v[86:89], v[146:149], v[224:227], v[86:89]
	v_mfma_f32_16x16x32_bf16 v[82:85], v[154:157], v[224:227], v[82:85]
	v_mfma_f32_16x16x32_bf16 v[70:73], v[146:149], v[232:235], v[70:73]
	v_mfma_f32_16x16x32_bf16 v[66:69], v[154:157], v[232:235], v[66:69]
	v_mfma_f32_16x16x32_bf16 v[118:121], v[150:153], v[182:185], v[118:121]
	v_mfma_f32_16x16x32_bf16 v[114:117], v[158:161], v[182:185], v[114:117]
	v_mfma_f32_16x16x32_bf16 v[102:105], v[150:153], v[220:223], v[102:105]
	v_mfma_f32_16x16x32_bf16 v[98:101], v[158:161], v[220:223], v[98:101]
	v_mfma_f32_16x16x32_bf16 v[86:89], v[150:153], v[228:231], v[86:89]
	v_mfma_f32_16x16x32_bf16 v[82:85], v[158:161], v[228:231], v[82:85]
	v_mfma_f32_16x16x32_bf16 v[70:73], v[150:153], v[236:239], v[70:73]
	v_mfma_f32_16x16x32_bf16 v[66:69], v[158:161], v[236:239], v[66:69]
	s_setprio 0
	s_barrier
	s_add_i32 s50, s44, s37
	v_lshl_add_u64 v[194:195], s[30:31], 0, v[164:165]
	s_mov_b32 m0, s50
	ds_read_b128 v[178:181], v214 offset:16384
	ds_read_b128 v[182:185], v214 offset:17408
	ds_read_b128 v[216:219], v214 offset:18432
	ds_read_b128 v[220:223], v214 offset:19456
	ds_read_b128 v[224:227], v214 offset:20480
	ds_read_b128 v[228:231], v214 offset:21504
	ds_read_b128 v[232:235], v214 offset:22528
	ds_read_b128 v[236:239], v214 offset:23552
	global_load_lds_dwordx4 v[194:195], off
	s_add_i32 m0, s50, 0x2000
	s_add_u32 s50, s30, 0x40000
	v_lshl_add_u64 v[240:241], s[30:31], 0, v[168:169]
	s_addc_u32 s51, s31, 0
	s_add_i32 s52, s45, s37
	global_load_lds_dwordx4 v[240:241], off
	v_lshl_add_u64 v[242:243], s[50:51], 0, v[164:165]
	s_mov_b32 m0, s52
	v_lshl_add_u64 v[244:245], s[34:35], 0, v[166:167]
	global_load_lds_dwordx4 v[242:243], off
	v_lshl_add_u64 v[242:243], s[50:51], 0, v[168:169]
	s_add_i32 m0, s52, 0x2000
	s_nop 0
	global_load_lds_dwordx4 v[242:243], off
	v_lshl_add_u64 v[242:243], s[34:35], 0, v[162:163]
	s_mov_b32 m0, s25
	s_nop 0
	global_load_lds_dwordx4 v[242:243], off
	s_mov_b32 m0, s27
	s_nop 0
	global_load_lds_dwordx4 v[244:245], off
	s_waitcnt vmcnt(8)
	s_waitcnt lgkmcnt(0)
	s_barrier
	s_setprio 1
	s_waitcnt lgkmcnt(0)
	v_mfma_f32_16x16x32_bf16 v[62:65], v[130:133], v[178:181], v[62:65]
	v_mfma_f32_16x16x32_bf16 v[58:61], v[138:141], v[178:181], v[58:61]
	v_mfma_f32_16x16x32_bf16 v[46:49], v[130:133], v[216:219], v[46:49]
	v_mfma_f32_16x16x32_bf16 v[42:45], v[138:141], v[216:219], v[42:45]
	v_mfma_f32_16x16x32_bf16 v[30:33], v[130:133], v[224:227], v[30:33]
	v_mfma_f32_16x16x32_bf16 v[26:29], v[138:141], v[224:227], v[26:29]
	v_mfma_f32_16x16x32_bf16 v[14:17], v[130:133], v[232:235], v[14:17]
	v_mfma_f32_16x16x32_bf16 v[10:13], v[138:141], v[232:235], v[10:13]
	v_mfma_f32_16x16x32_bf16 v[62:65], v[134:137], v[182:185], v[62:65]
	v_mfma_f32_16x16x32_bf16 v[58:61], v[142:145], v[182:185], v[58:61]
	v_mfma_f32_16x16x32_bf16 v[46:49], v[134:137], v[220:223], v[46:49]
	v_mfma_f32_16x16x32_bf16 v[42:45], v[142:145], v[220:223], v[42:45]
	v_mfma_f32_16x16x32_bf16 v[30:33], v[134:137], v[228:231], v[30:33]
	v_mfma_f32_16x16x32_bf16 v[26:29], v[142:145], v[228:231], v[26:29]
	v_mfma_f32_16x16x32_bf16 v[14:17], v[134:137], v[236:239], v[14:17]
	v_mfma_f32_16x16x32_bf16 v[10:13], v[142:145], v[236:239], v[10:13]
	s_setprio 0
	s_setprio 1
	v_mfma_f32_16x16x32_bf16 v[54:57], v[146:149], v[178:181], v[54:57]
	v_mfma_f32_16x16x32_bf16 v[50:53], v[154:157], v[178:181], v[50:53]
	v_mfma_f32_16x16x32_bf16 v[38:41], v[146:149], v[216:219], v[38:41]
	v_mfma_f32_16x16x32_bf16 v[34:37], v[154:157], v[216:219], v[34:37]
	v_mfma_f32_16x16x32_bf16 v[22:25], v[146:149], v[224:227], v[22:25]
	v_mfma_f32_16x16x32_bf16 v[18:21], v[154:157], v[224:227], v[18:21]
	v_mfma_f32_16x16x32_bf16 v[6:9], v[146:149], v[232:235], v[6:9]
	v_mfma_f32_16x16x32_bf16 v[2:5], v[154:157], v[232:235], v[2:5]
	v_mfma_f32_16x16x32_bf16 v[54:57], v[150:153], v[182:185], v[54:57]
	v_mfma_f32_16x16x32_bf16 v[50:53], v[158:161], v[182:185], v[50:53]
	v_mfma_f32_16x16x32_bf16 v[38:41], v[150:153], v[220:223], v[38:41]
	v_mfma_f32_16x16x32_bf16 v[34:37], v[158:161], v[220:223], v[34:37]
	v_mfma_f32_16x16x32_bf16 v[22:25], v[150:153], v[228:231], v[22:25]
	v_mfma_f32_16x16x32_bf16 v[18:21], v[158:161], v[228:231], v[18:21]
	v_mfma_f32_16x16x32_bf16 v[6:9], v[150:153], v[236:239], v[6:9]
	v_mfma_f32_16x16x32_bf16 v[2:5], v[158:161], v[236:239], v[2:5]
	s_setprio 0
	s_barrier
	s_add_i32 s50, 0, 0x18000
	s_add_i32 s51, 0, 0x1c000
	v_add_u32_e32 v142, s50, v191
	v_add_u32_e32 v158, s51, v191
	ds_read_b128 v[130:133], v142
	ds_read_b128 v[134:137], v142 offset:1024
	ds_read_b128 v[138:141], v142 offset:2048
	ds_read_b128 v[142:145], v142 offset:3072
	ds_read_b128 v[146:149], v158
	ds_read_b128 v[150:153], v158 offset:1024
	ds_read_b128 v[154:157], v158 offset:2048
	ds_read_b128 v[158:161], v158 offset:3072
	s_add_u32 s34, s34, 0x40000
	s_addc_u32 s35, s35, 0
	s_mov_b32 m0, s38
	v_lshl_add_u64 v[246:247], s[34:35], 0, v[162:163]
	ds_read_b128 v[178:181], v214 offset:32768
	ds_read_b128 v[182:185], v214 offset:33792
	ds_read_b128 v[216:219], v214 offset:34816
	ds_read_b128 v[220:223], v214 offset:35840
	ds_read_b128 v[224:227], v214 offset:36864
	ds_read_b128 v[228:231], v214 offset:37888
	ds_read_b128 v[232:235], v214 offset:38912
	ds_read_b128 v[236:239], v214 offset:39936
	global_load_lds_dwordx4 v[246:247], off
	v_lshl_add_u64 v[246:247], s[34:35], 0, v[166:167]
	s_mov_b32 m0, s39
	s_nop 0
	global_load_lds_dwordx4 v[246:247], off
	s_waitcnt vmcnt(8)
	s_waitcnt lgkmcnt(0)
	s_barrier
	s_setprio 1
	s_waitcnt lgkmcnt(0)
	v_mfma_f32_16x16x32_bf16 v[126:129], v[130:133], v[178:181], v[126:129]
	v_mfma_f32_16x16x32_bf16 v[122:125], v[138:141], v[178:181], v[122:125]
	v_mfma_f32_16x16x32_bf16 v[110:113], v[130:133], v[216:219], v[110:113]
	v_mfma_f32_16x16x32_bf16 v[106:109], v[138:141], v[216:219], v[106:109]
	v_mfma_f32_16x16x32_bf16 v[94:97], v[130:133], v[224:227], v[94:97]
	v_mfma_f32_16x16x32_bf16 v[90:93], v[138:141], v[224:227], v[90:93]
	v_mfma_f32_16x16x32_bf16 v[78:81], v[130:133], v[232:235], v[78:81]
	v_mfma_f32_16x16x32_bf16 v[74:77], v[138:141], v[232:235], v[74:77]
	v_mfma_f32_16x16x32_bf16 v[126:129], v[134:137], v[182:185], v[126:129]
	v_mfma_f32_16x16x32_bf16 v[122:125], v[142:145], v[182:185], v[122:125]
	v_mfma_f32_16x16x32_bf16 v[110:113], v[134:137], v[220:223], v[110:113]
	v_mfma_f32_16x16x32_bf16 v[106:109], v[142:145], v[220:223], v[106:109]
	v_mfma_f32_16x16x32_bf16 v[94:97], v[134:137], v[228:231], v[94:97]
	v_mfma_f32_16x16x32_bf16 v[90:93], v[142:145], v[228:231], v[90:93]
	v_mfma_f32_16x16x32_bf16 v[78:81], v[134:137], v[236:239], v[78:81]
	v_mfma_f32_16x16x32_bf16 v[74:77], v[142:145], v[236:239], v[74:77]
	s_setprio 0
	s_setprio 1
	v_mfma_f32_16x16x32_bf16 v[118:121], v[146:149], v[178:181], v[118:121]
	v_mfma_f32_16x16x32_bf16 v[114:117], v[154:157], v[178:181], v[114:117]
	v_mfma_f32_16x16x32_bf16 v[102:105], v[146:149], v[216:219], v[102:105]
	v_mfma_f32_16x16x32_bf16 v[98:101], v[154:157], v[216:219], v[98:101]
	v_mfma_f32_16x16x32_bf16 v[86:89], v[146:149], v[224:227], v[86:89]
	v_mfma_f32_16x16x32_bf16 v[82:85], v[154:157], v[224:227], v[82:85]
	v_mfma_f32_16x16x32_bf16 v[70:73], v[146:149], v[232:235], v[70:73]
	v_mfma_f32_16x16x32_bf16 v[66:69], v[154:157], v[232:235], v[66:69]
	v_mfma_f32_16x16x32_bf16 v[118:121], v[150:153], v[182:185], v[118:121]
	v_mfma_f32_16x16x32_bf16 v[114:117], v[158:161], v[182:185], v[114:117]
	v_mfma_f32_16x16x32_bf16 v[102:105], v[150:153], v[220:223], v[102:105]
	v_mfma_f32_16x16x32_bf16 v[98:101], v[158:161], v[220:223], v[98:101]
	v_mfma_f32_16x16x32_bf16 v[86:89], v[150:153], v[228:231], v[86:89]
	v_mfma_f32_16x16x32_bf16 v[82:85], v[158:161], v[228:231], v[82:85]
	v_mfma_f32_16x16x32_bf16 v[70:73], v[150:153], v[236:239], v[70:73]
	v_mfma_f32_16x16x32_bf16 v[66:69], v[158:161], v[236:239], v[66:69]
	s_setprio 0
	s_barrier
	s_add_i32 s34, s50, s37
	v_lshl_add_u64 v[194:195], v[194:195], 0, s[0:1]
	s_mov_b32 m0, s34
	ds_read_b128 v[178:181], v214 offset:49152
	ds_read_b128 v[182:185], v214 offset:50176
	ds_read_b128 v[216:219], v214 offset:51200
	ds_read_b128 v[220:223], v214 offset:52224
	ds_read_b128 v[224:227], v214 offset:53248
	ds_read_b128 v[228:231], v214 offset:54272
	ds_read_b128 v[232:235], v214 offset:55296
	ds_read_b128 v[236:239], v214 offset:56320
	global_load_lds_dwordx4 v[194:195], off
	s_add_i32 m0, s34, 0x2000
	s_add_u32 s30, s30, 0x40080
	v_lshl_add_u64 v[194:195], v[240:241], 0, s[0:1]
	s_addc_u32 s31, s31, 0
	s_add_i32 s34, s51, s37
	global_load_lds_dwordx4 v[194:195], off
	v_lshl_add_u64 v[194:195], s[30:31], 0, v[164:165]
	s_mov_b32 m0, s34
	s_nop 0
	global_load_lds_dwordx4 v[194:195], off
	v_lshl_add_u64 v[194:195], s[30:31], 0, v[168:169]
	s_add_i32 m0, s34, 0x2000
	s_nop 0
	global_load_lds_dwordx4 v[194:195], off
	v_lshl_add_u64 v[194:195], v[242:243], 0, s[0:1]
	s_mov_b32 m0, s41
	s_nop 0
	global_load_lds_dwordx4 v[194:195], off
	v_lshl_add_u64 v[194:195], v[244:245], 0, s[0:1]
	s_mov_b32 m0, s42
	s_nop 0
	global_load_lds_dwordx4 v[194:195], off
	s_waitcnt vmcnt(8)
	s_waitcnt lgkmcnt(0)
	s_barrier
	s_setprio 1
	s_waitcnt lgkmcnt(0)
	v_mfma_f32_16x16x32_bf16 v[62:65], v[130:133], v[178:181], v[62:65]
	v_mfma_f32_16x16x32_bf16 v[58:61], v[138:141], v[178:181], v[58:61]
	v_mfma_f32_16x16x32_bf16 v[46:49], v[130:133], v[216:219], v[46:49]
	v_mfma_f32_16x16x32_bf16 v[42:45], v[138:141], v[216:219], v[42:45]
	v_mfma_f32_16x16x32_bf16 v[30:33], v[130:133], v[224:227], v[30:33]
	v_mfma_f32_16x16x32_bf16 v[26:29], v[138:141], v[224:227], v[26:29]
	v_mfma_f32_16x16x32_bf16 v[14:17], v[130:133], v[232:235], v[14:17]
	v_mfma_f32_16x16x32_bf16 v[10:13], v[138:141], v[232:235], v[10:13]
	v_mfma_f32_16x16x32_bf16 v[62:65], v[134:137], v[182:185], v[62:65]
	v_mfma_f32_16x16x32_bf16 v[58:61], v[142:145], v[182:185], v[58:61]
	v_mfma_f32_16x16x32_bf16 v[46:49], v[134:137], v[220:223], v[46:49]
	v_mfma_f32_16x16x32_bf16 v[42:45], v[142:145], v[220:223], v[42:45]
	v_mfma_f32_16x16x32_bf16 v[30:33], v[134:137], v[228:231], v[30:33]
	v_mfma_f32_16x16x32_bf16 v[26:29], v[142:145], v[228:231], v[26:29]
	v_mfma_f32_16x16x32_bf16 v[14:17], v[134:137], v[236:239], v[14:17]
	v_mfma_f32_16x16x32_bf16 v[10:13], v[142:145], v[236:239], v[10:13]
	s_setprio 0
	s_setprio 1
	v_mfma_f32_16x16x32_bf16 v[54:57], v[146:149], v[178:181], v[54:57]
	v_mfma_f32_16x16x32_bf16 v[50:53], v[154:157], v[178:181], v[50:53]
	v_mfma_f32_16x16x32_bf16 v[38:41], v[146:149], v[216:219], v[38:41]
	v_mfma_f32_16x16x32_bf16 v[34:37], v[154:157], v[216:219], v[34:37]
	v_mfma_f32_16x16x32_bf16 v[22:25], v[146:149], v[224:227], v[22:25]
	v_mfma_f32_16x16x32_bf16 v[18:21], v[154:157], v[224:227], v[18:21]
	v_mfma_f32_16x16x32_bf16 v[6:9], v[146:149], v[232:235], v[6:9]
	v_mfma_f32_16x16x32_bf16 v[2:5], v[154:157], v[232:235], v[2:5]
	v_mfma_f32_16x16x32_bf16 v[54:57], v[150:153], v[182:185], v[54:57]
	v_mfma_f32_16x16x32_bf16 v[50:53], v[158:161], v[182:185], v[50:53]
	v_mfma_f32_16x16x32_bf16 v[38:41], v[150:153], v[220:223], v[38:41]
	v_mfma_f32_16x16x32_bf16 v[34:37], v[158:161], v[220:223], v[34:37]
	v_mfma_f32_16x16x32_bf16 v[22:25], v[150:153], v[228:231], v[22:25]
	v_mfma_f32_16x16x32_bf16 v[18:21], v[158:161], v[228:231], v[18:21]
	v_mfma_f32_16x16x32_bf16 v[6:9], v[150:153], v[236:239], v[6:9]
	v_mfma_f32_16x16x32_bf16 v[2:5], v[158:161], v[236:239], v[2:5]
	s_setprio 0
	s_barrier
	s_add_i32 s49, s49, 2
	s_add_u32 s28, s28, 0x100
	s_addc_u32 s29, s29, 0
	s_add_u32 s47, s47, 0x100
	s_addc_u32 s48, s48, 0
	s_cmp_gt_u32 s49, 13
	s_cbranch_scc0 .LBB0_762
	v_lshl_or_b32 v138, s24, 8, v211
	v_lshl_add_u32 v184, s26, 8, v1
	v_ashrrev_i32_e32 v139, 31, v138
	v_lshlrev_b64 v[182:183], 1, v[138:139]
	v_ashrrev_i32_e32 v185, 31, v184
	v_lshl_add_u64 v[146:147], s[82:83], 0, v[182:183]
	v_lshlrev_b64 v[134:135], 11, v[184:185]
	v_readlane_b32 s48, v251, 6
	v_lshl_add_u64 v[150:151], v[146:147], 0, v[134:135]
	v_readlane_b32 s58, v251, 16
	v_readlane_b32 s59, v251, 17
	v_lshl_add_u64 v[148:149], s[18:19], 0, v[182:183]
	global_load_dwordx4 v[130:133], v[150:151], off nt
	v_lshlrev_b64 v[180:181], 2, v[138:139]
	s_mov_b64 s[46:47], s[58:59]
	v_lshl_add_u64 v[152:153], v[148:149], 0, v[134:135]
	v_lshl_add_u64 v[178:179], s[46:47], 0, v[180:181]
	global_load_dwordx4 v[134:137], v[152:153], off
	global_load_dwordx4 v[162:165], v[178:179], off
	global_load_dwordx4 v[166:169], v[178:179], off offset:16
	global_load_dwordx4 v[170:173], v[178:179], off offset:512
	global_load_dwordx4 v[174:177], v[178:179], off offset:528
	ds_read_b32 v215, v193
	ds_read_b32 v186, v196
	ds_read_b32 v216, v197
	ds_read_b32 v190, v198
	ds_read_b32 v218, v199
	ds_read_b32 v192, v200
	ds_read_b32 v217, v201
	ds_read_b32 v188, v202
	s_waitcnt lgkmcnt(0)
	v_mul_f32_e32 v215, 0xbfb8aa3b, v215
	v_mul_f32_e32 v126, v126, v215
	v_mul_f32_e32 v122, v122, v215
	v_mul_f32_e32 v127, v127, v215
	v_mul_f32_e32 v123, v123, v215
	v_mul_f32_e32 v124, v124, v215
	v_exp_f32_e32 v126, v126
	v_exp_f32_e32 v122, v122
	v_exp_f32_e32 v127, v127
	v_exp_f32_e32 v123, v123
	v_exp_f32_e32 v124, v124
	v_mul_f32_e32 v128, v128, v215
	v_mul_f32_e32 v129, v129, v215
	v_mul_f32_e32 v125, v125, v215
	v_exp_f32_e32 v128, v128
	v_exp_f32_e32 v129, v129
	v_exp_f32_e32 v219, v125
	v_add_f32_e32 v125, 1.0, v126
	v_add_f32_e32 v126, 1.0, v122
	v_add_f32_e32 v127, 1.0, v127
	v_add_f32_e32 v242, 1.0, v123
	v_add_f32_e32 v243, 1.0, v124
	v_rcp_f32_e32 v122, v125
	v_rcp_f32_e32 v124, v126
	v_rcp_f32_e32 v123, v127
	v_rcp_f32_e32 v125, v242
	v_add_f32_e32 v128, 1.0, v128
	v_add_f32_e32 v129, 1.0, v129
	v_rcp_f32_e32 v128, v128
	v_rcp_f32_e32 v129, v129
	v_rcp_f32_e32 v242, v243
	v_or_b32_e32 v194, 32, v184
	v_readlane_b32 s49, v251, 7
	v_readlane_b32 s50, v251, 8
	v_readlane_b32 s51, v251, 9
	v_readlane_b32 s60, v251, 18
	v_readlane_b32 s61, v251, 19
	v_or_b32_e32 v236, 16, v184
	v_ashrrev_i32_e32 v195, 31, v194
	v_readlane_b32 s62, v251, 20
	v_readlane_b32 s63, v251, 21
	s_mov_b64 s[48:49], s[60:61]
	v_ashrrev_i32_e32 v237, 31, v236
	v_lshlrev_b64 v[156:157], 11, v[194:195]
	v_lshlrev_b64 v[154:155], 11, v[236:237]
	v_lshl_add_u64 v[238:239], s[82:83], 0, v[156:157]
	v_lshl_add_u64 v[146:147], v[146:147], 0, v[154:155]
	v_lshl_add_u64 v[148:149], v[148:149], 0, v[154:155]
	v_lshl_add_u64 v[240:241], s[18:19], 0, v[156:157]
	v_lshl_add_u64 v[238:239], v[238:239], 0, v[182:183]
	global_load_dwordx4 v[220:223], v[150:151], off offset:256 nt
	global_load_dwordx4 v[224:227], v[152:153], off offset:256
	global_load_dwordx4 v[228:231], v[146:147], off nt
	global_load_dwordx4 v[154:157], v[146:147], off offset:256 nt
	global_load_dwordx4 v[232:235], v[148:149], off
	global_load_dwordx4 v[158:161], v[148:149], off offset:256
	v_lshl_add_u64 v[240:241], v[240:241], 0, v[182:183]
	global_load_dwordx4 v[150:153], v[238:239], off nt
	global_load_dwordx4 v[146:149], v[240:241], off
	v_mul_f32_e32 v118, v118, v215
	v_mul_f32_e32 v119, v119, v215
	v_mul_f32_e32 v120, v120, v215
	v_mul_f32_e32 v121, v121, v215
	v_mul_f32_e32 v114, v114, v215
	v_mul_f32_e32 v115, v115, v215
	v_mul_f32_e32 v116, v116, v215
	v_mul_f32_e32 v117, v117, v215
	v_exp_f32_e32 v118, v118
	v_exp_f32_e32 v119, v119
	v_exp_f32_e32 v120, v120
	v_exp_f32_e32 v121, v121
	v_exp_f32_e32 v114, v114
	v_exp_f32_e32 v115, v115
	v_exp_f32_e32 v116, v116
	v_exp_f32_e32 v117, v117
	v_add_f32_e32 v118, 1.0, v118
	v_add_f32_e32 v119, 1.0, v119
	v_add_f32_e32 v120, 1.0, v120
	s_waitcnt vmcnt(13)
	v_lshlrev_b32_e32 v126, 16, v130
	v_and_b32_e32 v127, 0xffff0000, v130
	v_lshlrev_b32_e32 v246, 16, v132
	v_and_b32_e32 v247, 0xffff0000, v132
	v_pk_mul_f32 v[126:127], v[186:187], v[126:127] op_sel_hi:[0,1]
	v_pk_mul_f32 v[246:247], v[186:187], v[246:247] op_sel_hi:[0,1]
	s_waitcnt vmcnt(12)
	v_lshlrev_b32_e32 v244, 16, v134
	v_and_b32_e32 v245, 0xffff0000, v134
	v_lshlrev_b32_e32 v248, 16, v136
	v_and_b32_e32 v249, 0xffff0000, v136
	s_waitcnt vmcnt(11)
	v_pk_mul_f32 v[126:127], v[126:127], v[162:163]
	s_waitcnt vmcnt(10)
	v_pk_mul_f32 v[138:139], v[246:247], v[166:167]
	v_pk_fma_f32 v[122:123], v[122:123], v[126:127], v[244:245]
	v_pk_fma_f32 v[126:127], v[124:125], v[138:139], v[248:249]
	v_add_f32_e32 v124, 1.0, v219
	v_rcp_f32_e32 v243, v124
	v_lshlrev_b32_e32 v124, 16, v131
	v_and_b32_e32 v125, 0xffff0000, v131
	v_pk_mul_f32 v[124:125], v[186:187], v[124:125] op_sel_hi:[0,1]
	v_lshlrev_b32_e32 v130, 16, v135
	v_and_b32_e32 v131, 0xffff0000, v135
	v_pk_mul_f32 v[124:125], v[124:125], v[164:165]
	v_add_f32_e32 v121, 1.0, v121
	v_pk_fma_f32 v[124:125], v[128:129], v[124:125], v[130:131]
	v_lshlrev_b32_e32 v128, 16, v133
	v_and_b32_e32 v129, 0xffff0000, v133
	v_pk_mul_f32 v[128:129], v[186:187], v[128:129] op_sel_hi:[0,1]
	v_lshlrev_b32_e32 v130, 16, v137
	v_and_b32_e32 v131, 0xffff0000, v137
	v_pk_mul_f32 v[128:129], v[128:129], v[168:169]
	v_add_f32_e32 v114, 1.0, v114
	v_pk_fma_f32 v[128:129], v[242:243], v[128:129], v[130:131]
	v_lshlrev_b64 v[130:131], 12, v[184:185]
	v_lshl_add_u64 v[130:131], s[48:49], 0, v[130:131]
	v_lshl_add_u64 v[130:131], v[130:131], 0, v[180:181]
	global_store_dwordx4 v[130:131], v[122:125], off
	global_store_dwordx4 v[130:131], v[126:129], off offset:16
	s_nop 0
	v_add_f32_e32 v115, 1.0, v115
	v_add_f32_e32 v116, 1.0, v116
	v_add_f32_e32 v117, 1.0, v117
	v_rcp_f32_e32 v132, v118
	v_rcp_f32_e32 v133, v119
	v_rcp_f32_e32 v136, v120
	v_rcp_f32_e32 v137, v121
	v_rcp_f32_e32 v134, v114
	v_rcp_f32_e32 v135, v115
	v_rcp_f32_e32 v138, v116
	v_rcp_f32_e32 v139, v117
	v_mul_f32_e32 v185, 0xbfb8aa3b, v216
	v_mul_f32_e32 v110, v110, v185
	v_mul_f32_e32 v111, v111, v185
	v_mul_f32_e32 v112, v112, v185
	v_mul_f32_e32 v113, v113, v185
	s_waitcnt vmcnt(9)
	v_lshlrev_b32_e32 v114, 16, v220
	v_and_b32_e32 v115, 0xffff0000, v220
	v_lshlrev_b32_e32 v118, 16, v221
	v_and_b32_e32 v119, 0xffff0000, v221
	v_lshlrev_b32_e32 v116, 16, v222
	v_and_b32_e32 v117, 0xffff0000, v222
	s_waitcnt vmcnt(8)
	v_lshlrev_b32_e32 v142, 16, v226
	v_and_b32_e32 v143, 0xffff0000, v226
	v_lshlrev_b32_e32 v120, 16, v223
	v_and_b32_e32 v121, 0xffff0000, v223
	v_lshlrev_b32_e32 v220, 16, v227
	v_and_b32_e32 v221, 0xffff0000, v227
	v_pk_mul_f32 v[222:223], v[186:187], v[114:115] op_sel_hi:[0,1]
	v_pk_mul_f32 v[226:227], v[186:187], v[118:119] op_sel_hi:[0,1]
	v_lshlrev_b32_e32 v140, 16, v224
	v_and_b32_e32 v141, 0xffff0000, v224
	v_lshlrev_b32_e32 v144, 16, v225
	v_and_b32_e32 v145, 0xffff0000, v225
	v_pk_mul_f32 v[224:225], v[186:187], v[116:117] op_sel_hi:[0,1]
	v_pk_mul_f32 v[242:243], v[186:187], v[120:121] op_sel_hi:[0,1]
	global_load_dwordx4 v[118:121], v[238:239], off offset:256 nt
	global_load_dwordx4 v[114:117], v[240:241], off offset:256
	v_mul_f32_e32 v106, v106, v185
	v_mul_f32_e32 v107, v107, v185
	v_mul_f32_e32 v108, v108, v185
	v_mul_f32_e32 v109, v109, v185
	v_exp_f32_e32 v110, v110
	v_exp_f32_e32 v111, v111
	v_exp_f32_e32 v112, v112
	v_exp_f32_e32 v113, v113
	v_exp_f32_e32 v106, v106
	v_exp_f32_e32 v107, v107
	v_exp_f32_e32 v108, v108
	v_exp_f32_e32 v109, v109
	v_add_f32_e32 v110, 1.0, v110
	v_add_f32_e32 v111, 1.0, v111
	v_add_f32_e32 v112, 1.0, v112
	v_add_f32_e32 v113, 1.0, v113
	v_add_f32_e32 v106, 1.0, v106
	v_add_f32_e32 v107, 1.0, v107
	v_add_f32_e32 v108, 1.0, v108
	v_add_f32_e32 v109, 1.0, v109
	v_mul_f32_e32 v102, v102, v185
	v_mul_f32_e32 v103, v103, v185
	v_mul_f32_e32 v104, v104, v185
	v_mul_f32_e32 v105, v105, v185
	v_mul_f32_e32 v98, v98, v185
	v_mul_f32_e32 v99, v99, v185
	v_mul_f32_e32 v100, v100, v185
	v_mul_f32_e32 v101, v101, v185
	v_exp_f32_e32 v102, v102
	v_exp_f32_e32 v103, v103
	v_exp_f32_e32 v104, v104
	v_exp_f32_e32 v105, v105
	v_exp_f32_e32 v98, v98
	v_exp_f32_e32 v99, v99
	v_exp_f32_e32 v100, v100
	v_exp_f32_e32 v101, v101
	v_add_f32_e32 v102, 1.0, v102
	v_add_f32_e32 v103, 1.0, v103
	v_add_f32_e32 v104, 1.0, v104
	v_add_f32_e32 v105, 1.0, v105
	v_add_f32_e32 v98, 1.0, v98
	v_pk_mul_f32 v[122:123], v[222:223], v[170:171]
	v_pk_mul_f32 v[124:125], v[226:227], v[172:173]
	v_pk_mul_f32 v[126:127], v[224:225], v[174:175]
	v_pk_fma_f32 v[122:123], v[132:133], v[122:123], v[140:141]
	v_pk_fma_f32 v[124:125], v[136:137], v[124:125], v[144:145]
	v_pk_mul_f32 v[128:129], v[242:243], v[176:177]
	v_pk_fma_f32 v[126:127], v[134:135], v[126:127], v[142:143]
	v_pk_fma_f32 v[128:129], v[138:139], v[128:129], v[220:221]
	global_store_dwordx4 v[130:131], v[122:125], off offset:512
	global_store_dwordx4 v[130:131], v[126:129], off offset:528
	s_nop 0
	v_or_b32_e32 v124, 48, v184
	v_rcp_f32_e32 v138, v110
	v_rcp_f32_e32 v139, v111
	v_rcp_f32_e32 v142, v112
	v_rcp_f32_e32 v143, v113
	v_ashrrev_i32_e32 v125, 31, v124
	v_rcp_f32_e32 v140, v106
	v_rcp_f32_e32 v141, v107
	v_rcp_f32_e32 v144, v108
	v_rcp_f32_e32 v145, v109
	s_waitcnt vmcnt(11)
	v_lshlrev_b32_e32 v106, 16, v228
	v_and_b32_e32 v107, 0xffff0000, v228
	v_lshlrev_b32_e32 v110, 16, v229
	v_and_b32_e32 v111, 0xffff0000, v229
	v_lshlrev_b64 v[122:123], 11, v[124:125]
	v_lshlrev_b64 v[134:135], 12, v[236:237]
	s_waitcnt vmcnt(9)
	v_lshlrev_b32_e32 v220, 16, v232
	v_and_b32_e32 v221, 0xffff0000, v232
	v_lshlrev_b32_e32 v108, 16, v230
	v_and_b32_e32 v109, 0xffff0000, v230
	v_lshlrev_b32_e32 v224, 16, v233
	v_and_b32_e32 v225, 0xffff0000, v233
	v_lshlrev_b32_e32 v112, 16, v231
	v_and_b32_e32 v113, 0xffff0000, v231
	v_pk_mul_f32 v[228:229], v[190:191], v[106:107] op_sel_hi:[0,1]
	v_pk_mul_f32 v[232:233], v[190:191], v[110:111] op_sel_hi:[0,1]
	v_lshl_add_u64 v[136:137], s[82:83], 0, v[122:123]
	v_lshl_add_u64 v[134:135], s[48:49], 0, v[134:135]
	v_lshlrev_b32_e32 v222, 16, v234
	v_and_b32_e32 v223, 0xffff0000, v234
	v_lshlrev_b32_e32 v226, 16, v235
	v_and_b32_e32 v227, 0xffff0000, v235
	v_pk_mul_f32 v[230:231], v[190:191], v[108:109] op_sel_hi:[0,1]
	v_pk_mul_f32 v[234:235], v[190:191], v[112:113] op_sel_hi:[0,1]
	v_lshl_add_u64 v[122:123], s[18:19], 0, v[122:123]
	v_lshl_add_u64 v[136:137], v[136:137], 0, v[182:183]
	v_lshl_add_u64 v[134:135], v[134:135], 0, v[180:181]
	v_lshl_add_u64 v[122:123], v[122:123], 0, v[182:183]
	global_load_dwordx4 v[110:113], v[136:137], off nt
	global_load_dwordx4 v[106:109], v[122:123], off
	v_add_f32_e32 v99, 1.0, v99
	v_add_f32_e32 v100, 1.0, v100
	v_add_f32_e32 v101, 1.0, v101
	v_mul_f32_e32 v185, 0xbfb8aa3b, v218
	v_mul_f32_e32 v94, v94, v185
	v_mul_f32_e32 v95, v95, v185
	v_mul_f32_e32 v96, v96, v185
	v_mul_f32_e32 v97, v97, v185
	v_mul_f32_e32 v90, v90, v185
	v_mul_f32_e32 v91, v91, v185
	v_mul_f32_e32 v92, v92, v185
	v_mul_f32_e32 v93, v93, v185
	v_exp_f32_e32 v94, v94
	v_exp_f32_e32 v95, v95
	v_exp_f32_e32 v96, v96
	v_exp_f32_e32 v97, v97
	v_exp_f32_e32 v90, v90
	v_exp_f32_e32 v91, v91
	v_exp_f32_e32 v92, v92
	v_exp_f32_e32 v93, v93
	v_add_f32_e32 v94, 1.0, v94
	v_add_f32_e32 v95, 1.0, v95
	v_add_f32_e32 v96, 1.0, v96
	v_add_f32_e32 v97, 1.0, v97
	v_add_f32_e32 v90, 1.0, v90
	v_add_f32_e32 v91, 1.0, v91
	v_add_f32_e32 v92, 1.0, v92
	v_add_f32_e32 v93, 1.0, v93
	v_mul_f32_e32 v86, v86, v185
	v_mul_f32_e32 v82, v82, v185
	v_mul_f32_e32 v87, v87, v185
	v_mul_f32_e32 v83, v83, v185
	v_mul_f32_e32 v88, v88, v185
	v_mul_f32_e32 v89, v89, v185
	v_mul_f32_e32 v84, v84, v185
	v_mul_f32_e32 v85, v85, v185
	v_exp_f32_e32 v86, v86
	v_exp_f32_e32 v82, v82
	v_exp_f32_e32 v87, v87
	v_pk_mul_f32 v[126:127], v[228:229], v[162:163]
	v_pk_mul_f32 v[128:129], v[232:233], v[164:165]
	v_pk_mul_f32 v[130:131], v[230:231], v[166:167]
	v_pk_mul_f32 v[132:133], v[234:235], v[168:169]
	v_pk_fma_f32 v[126:127], v[138:139], v[126:127], v[220:221]
	v_pk_fma_f32 v[128:129], v[142:143], v[128:129], v[224:225]
	v_pk_fma_f32 v[130:131], v[140:141], v[130:131], v[222:223]
	v_pk_fma_f32 v[132:133], v[144:145], v[132:133], v[226:227]
	global_store_dwordx4 v[134:135], v[126:129], off
	global_store_dwordx4 v[134:135], v[130:133], off offset:16
	s_nop 0
	v_rcp_f32_e32 v138, v102
	v_rcp_f32_e32 v139, v103
	v_rcp_f32_e32 v142, v104
	v_rcp_f32_e32 v143, v105
	v_rcp_f32_e32 v140, v98
	v_rcp_f32_e32 v141, v99
	v_rcp_f32_e32 v144, v100
	v_rcp_f32_e32 v145, v101
	v_lshlrev_b32_e32 v98, 16, v154
	v_and_b32_e32 v99, 0xffff0000, v154
	v_lshlrev_b32_e32 v102, 16, v155
	v_and_b32_e32 v103, 0xffff0000, v155
	s_waitcnt vmcnt(12)
	v_lshlrev_b32_e32 v220, 16, v158
	v_and_b32_e32 v221, 0xffff0000, v158
	v_lshlrev_b32_e32 v100, 16, v156
	v_and_b32_e32 v101, 0xffff0000, v156
	v_lshlrev_b32_e32 v154, 16, v159
	v_and_b32_e32 v155, 0xffff0000, v159
	v_lshlrev_b32_e32 v104, 16, v157
	v_and_b32_e32 v105, 0xffff0000, v157
	v_pk_mul_f32 v[158:159], v[190:191], v[98:99] op_sel_hi:[0,1]
	v_pk_mul_f32 v[224:225], v[190:191], v[102:103] op_sel_hi:[0,1]
	v_lshlrev_b32_e32 v222, 16, v160
	v_and_b32_e32 v223, 0xffff0000, v160
	v_lshlrev_b32_e32 v156, 16, v161
	v_and_b32_e32 v157, 0xffff0000, v161
	v_pk_mul_f32 v[160:161], v[190:191], v[100:101] op_sel_hi:[0,1]
	v_pk_mul_f32 v[226:227], v[190:191], v[104:105] op_sel_hi:[0,1]
	global_load_dwordx4 v[102:105], v[136:137], off offset:256 nt
	global_load_dwordx4 v[98:101], v[122:123], off offset:256
	v_lshlrev_b64 v[136:137], 12, v[194:195]
	v_lshl_add_u64 v[136:137], s[48:49], 0, v[136:137]
	v_lshl_add_u64 v[136:137], v[136:137], 0, v[180:181]
	v_exp_f32_e32 v83, v83
	v_exp_f32_e32 v88, v88
	v_exp_f32_e32 v89, v89
	v_exp_f32_e32 v84, v84
	v_exp_f32_e32 v85, v85
	v_add_f32_e32 v86, 1.0, v86
	v_add_f32_e32 v82, 1.0, v82
	v_add_f32_e32 v87, 1.0, v87
	v_add_f32_e32 v83, 1.0, v83
	v_add_f32_e32 v88, 1.0, v88
	v_add_f32_e32 v89, 1.0, v89
	v_add_f32_e32 v84, 1.0, v84
	v_add_f32_e32 v85, 1.0, v85
	v_lshlrev_b64 v[124:125], 12, v[124:125]
	v_lshl_add_u64 v[124:125], s[48:49], 0, v[124:125]
	v_lshl_add_u64 v[124:125], v[124:125], 0, v[180:181]
	s_and_b64 vcc, exec, s[4:5]
	s_mov_b32 s24, s6
	s_mov_b32 s26, s8
	s_mov_b64 s[30:31], s[22:23]
	s_mov_b64 s[28:29], s[20:21]
	v_readlane_b32 s52, v251, 10
	v_readlane_b32 s53, v251, 11
	v_readlane_b32 s54, v251, 12
	v_readlane_b32 s55, v251, 13
	v_readlane_b32 s56, v251, 14
	v_readlane_b32 s57, v251, 15
	s_mov_b64 s[50:51], s[62:63]
	v_pk_mul_f32 v[122:123], v[158:159], v[170:171]
	v_pk_mul_f32 v[128:129], v[224:225], v[172:173]
	v_pk_mul_f32 v[130:131], v[160:161], v[174:175]
	v_pk_mul_f32 v[132:133], v[226:227], v[176:177]
	v_pk_fma_f32 v[126:127], v[138:139], v[122:123], v[220:221]
	v_pk_fma_f32 v[128:129], v[142:143], v[128:129], v[154:155]
	v_pk_fma_f32 v[130:131], v[140:141], v[130:131], v[222:223]
	v_pk_fma_f32 v[132:133], v[144:145], v[132:133], v[156:157]
	global_store_dwordx4 v[134:135], v[126:129], off offset:512
	global_store_dwordx4 v[134:135], v[130:133], off offset:528
	s_nop 0
	v_add_u32_e32 v122, 0x80, v184
	v_rcp_f32_e32 v140, v94
	v_rcp_f32_e32 v141, v95
	v_rcp_f32_e32 v144, v96
	v_rcp_f32_e32 v145, v97
	v_ashrrev_i32_e32 v123, 31, v122
	v_rcp_f32_e32 v142, v90
	v_rcp_f32_e32 v143, v91
	v_rcp_f32_e32 v154, v92
	v_rcp_f32_e32 v155, v93
	s_waitcnt vmcnt(15)
	v_lshlrev_b32_e32 v90, 16, v150
	v_and_b32_e32 v91, 0xffff0000, v150
	v_lshlrev_b32_e32 v94, 16, v151
	v_and_b32_e32 v95, 0xffff0000, v151
	v_lshlrev_b64 v[134:135], 11, v[122:123]
	v_lshlrev_b32_e32 v92, 16, v152
	v_and_b32_e32 v93, 0xffff0000, v152
	v_lshlrev_b32_e32 v96, 16, v153
	v_and_b32_e32 v97, 0xffff0000, v153
	v_pk_mul_f32 v[150:151], v[192:193], v[90:91] op_sel_hi:[0,1]
	v_pk_mul_f32 v[160:161], v[192:193], v[94:95] op_sel_hi:[0,1]
	v_lshl_add_u64 v[138:139], s[82:83], 0, v[134:135]
	s_waitcnt vmcnt(14)
	v_lshlrev_b32_e32 v156, 16, v146
	v_and_b32_e32 v157, 0xffff0000, v146
	v_lshlrev_b32_e32 v146, 16, v147
	v_and_b32_e32 v147, 0xffff0000, v147
	v_pk_mul_f32 v[152:153], v[192:193], v[92:93] op_sel_hi:[0,1]
	v_pk_mul_f32 v[194:195], v[192:193], v[96:97] op_sel_hi:[0,1]
	v_lshl_add_u64 v[134:135], s[18:19], 0, v[134:135]
	v_lshl_add_u64 v[138:139], v[138:139], 0, v[182:183]
	v_lshlrev_b32_e32 v158, 16, v148
	v_and_b32_e32 v159, 0xffff0000, v148
	v_lshlrev_b32_e32 v148, 16, v149
	v_and_b32_e32 v149, 0xffff0000, v149
	v_lshl_add_u64 v[134:135], v[134:135], 0, v[182:183]
	global_load_dwordx4 v[94:97], v[138:139], off nt
	global_load_dwordx4 v[90:93], v[134:135], off
	v_pk_mul_f32 v[126:127], v[150:151], v[162:163]
	v_pk_mul_f32 v[128:129], v[160:161], v[164:165]
	v_pk_mul_f32 v[130:131], v[152:153], v[166:167]
	v_pk_mul_f32 v[132:133], v[194:195], v[168:169]
	v_pk_fma_f32 v[126:127], v[140:141], v[126:127], v[156:157]
	v_pk_fma_f32 v[128:129], v[144:145], v[128:129], v[146:147]
	v_pk_fma_f32 v[130:131], v[142:143], v[130:131], v[158:159]
	v_pk_fma_f32 v[132:133], v[154:155], v[132:133], v[148:149]
	global_store_dwordx4 v[136:137], v[126:129], off
	global_store_dwordx4 v[136:137], v[130:133], off offset:16
	s_nop 0
	v_rcp_f32_e32 v140, v86
	v_rcp_f32_e32 v142, v82
	v_rcp_f32_e32 v141, v87
	v_rcp_f32_e32 v143, v83
	v_rcp_f32_e32 v144, v88
	v_rcp_f32_e32 v145, v89
	v_rcp_f32_e32 v146, v84
	v_rcp_f32_e32 v147, v85
	s_waitcnt vmcnt(15)
	v_lshlrev_b32_e32 v82, 16, v118
	v_and_b32_e32 v83, 0xffff0000, v118
	v_lshlrev_b32_e32 v84, 16, v120
	v_and_b32_e32 v85, 0xffff0000, v120
	v_lshlrev_b32_e32 v86, 16, v119
	v_and_b32_e32 v87, 0xffff0000, v119
	s_waitcnt vmcnt(14)
	v_lshlrev_b32_e32 v148, 16, v114
	v_and_b32_e32 v149, 0xffff0000, v114
	v_lshlrev_b32_e32 v150, 16, v116
	v_and_b32_e32 v151, 0xffff0000, v116
	v_lshlrev_b32_e32 v152, 16, v115
	v_and_b32_e32 v153, 0xffff0000, v115
	v_lshlrev_b32_e32 v88, 16, v121
	v_and_b32_e32 v89, 0xffff0000, v121
	v_lshlrev_b32_e32 v120, 16, v117
	v_and_b32_e32 v121, 0xffff0000, v117
	v_pk_mul_f32 v[114:115], v[192:193], v[82:83] op_sel_hi:[0,1]
	v_pk_mul_f32 v[116:117], v[192:193], v[84:85] op_sel_hi:[0,1]
	v_pk_mul_f32 v[118:119], v[192:193], v[86:87] op_sel_hi:[0,1]
	v_pk_mul_f32 v[154:155], v[192:193], v[88:89] op_sel_hi:[0,1]
	global_load_dwordx4 v[86:89], v[138:139], off offset:256 nt
	global_load_dwordx4 v[82:85], v[134:135], off offset:256
	v_pk_mul_f32 v[114:115], v[114:115], v[170:171]
	v_pk_mul_f32 v[116:117], v[116:117], v[174:175]
	v_pk_mul_f32 v[126:127], v[118:119], v[172:173]
	v_pk_mul_f32 v[128:129], v[154:155], v[176:177]
	v_pk_fma_f32 v[114:115], v[140:141], v[114:115], v[148:149]
	v_pk_fma_f32 v[118:119], v[142:143], v[116:117], v[150:151]
	v_pk_fma_f32 v[116:117], v[144:145], v[126:127], v[152:153]
	v_pk_fma_f32 v[120:121], v[146:147], v[128:129], v[120:121]
	global_store_dwordx4 v[136:137], v[114:117], off offset:512
	global_store_dwordx4 v[136:137], v[118:121], off offset:528
	s_nop 0
	v_mul_f32_e32 v148, 0xbfb8aa3b, v217
	v_mul_f32_e32 v78, v78, v148
	v_mul_f32_e32 v74, v74, v148
	v_mul_f32_e32 v79, v79, v148
	v_mul_f32_e32 v75, v75, v148
	v_mul_f32_e32 v80, v80, v148
	v_mul_f32_e32 v81, v81, v148
	v_mul_f32_e32 v76, v76, v148
	v_mul_f32_e32 v77, v77, v148
	v_exp_f32_e32 v78, v78
	v_exp_f32_e32 v74, v74
	v_exp_f32_e32 v79, v79
	v_exp_f32_e32 v75, v75
	v_exp_f32_e32 v80, v80
	v_exp_f32_e32 v81, v81
	v_exp_f32_e32 v76, v76
	v_exp_f32_e32 v77, v77
	v_add_f32_e32 v78, 1.0, v78
	v_add_f32_e32 v74, 1.0, v74
	v_add_f32_e32 v79, 1.0, v79
	v_add_f32_e32 v75, 1.0, v75
	v_add_f32_e32 v80, 1.0, v80
	v_add_f32_e32 v81, 1.0, v81
	v_add_u32_e32 v114, 0x90, v184
	v_add_f32_e32 v76, 1.0, v76
	v_add_f32_e32 v77, 1.0, v77
	v_rcp_f32_e32 v132, v78
	v_rcp_f32_e32 v134, v74
	v_rcp_f32_e32 v133, v79
	v_rcp_f32_e32 v135, v75
	v_rcp_f32_e32 v136, v80
	v_rcp_f32_e32 v137, v81
	v_ashrrev_i32_e32 v115, 31, v114
	v_rcp_f32_e32 v138, v76
	v_rcp_f32_e32 v139, v77
	s_waitcnt vmcnt(15)
	v_lshlrev_b32_e32 v74, 16, v110
	v_and_b32_e32 v75, 0xffff0000, v110
	v_lshlrev_b32_e32 v76, 16, v112
	v_and_b32_e32 v77, 0xffff0000, v112
	v_lshlrev_b32_e32 v78, 16, v111
	v_and_b32_e32 v79, 0xffff0000, v111
	v_lshlrev_b64 v[120:121], 11, v[114:115]
	s_waitcnt vmcnt(14)
	v_lshlrev_b32_e32 v140, 16, v106
	v_and_b32_e32 v141, 0xffff0000, v106
	v_lshlrev_b32_e32 v142, 16, v108
	v_and_b32_e32 v143, 0xffff0000, v108
	v_lshlrev_b32_e32 v144, 16, v107
	v_and_b32_e32 v145, 0xffff0000, v107
	v_lshlrev_b32_e32 v80, 16, v113
	v_and_b32_e32 v81, 0xffff0000, v113
	v_lshlrev_b32_e32 v112, 16, v109
	v_and_b32_e32 v113, 0xffff0000, v109
	v_pk_mul_f32 v[106:107], v[188:189], v[74:75] op_sel_hi:[0,1]
	v_pk_mul_f32 v[108:109], v[188:189], v[76:77] op_sel_hi:[0,1]
	v_pk_mul_f32 v[110:111], v[188:189], v[78:79] op_sel_hi:[0,1]
	v_lshl_add_u64 v[130:131], s[82:83], 0, v[120:121]
	v_pk_mul_f32 v[146:147], v[188:189], v[80:81] op_sel_hi:[0,1]
	v_lshl_add_u64 v[120:121], s[18:19], 0, v[120:121]
	v_lshl_add_u64 v[130:131], v[130:131], 0, v[182:183]
	v_lshl_add_u64 v[120:121], v[120:121], 0, v[182:183]
	global_load_dwordx4 v[78:81], v[130:131], off nt
	global_load_dwordx4 v[74:77], v[120:121], off
	v_mul_f32_e32 v70, v70, v148
	v_mul_f32_e32 v66, v66, v148
	v_mul_f32_e32 v71, v71, v148
	v_mul_f32_e32 v67, v67, v148
	v_mul_f32_e32 v72, v72, v148
	v_mul_f32_e32 v73, v73, v148
	v_mul_f32_e32 v68, v68, v148
	v_mul_f32_e32 v69, v69, v148
	v_exp_f32_e32 v70, v70
	v_exp_f32_e32 v66, v66
	v_exp_f32_e32 v71, v71
	v_exp_f32_e32 v67, v67
	v_exp_f32_e32 v72, v72
	v_exp_f32_e32 v73, v73
	v_exp_f32_e32 v68, v68
	v_exp_f32_e32 v69, v69
	v_add_f32_e32 v70, 1.0, v70
	v_pk_mul_f32 v[106:107], v[106:107], v[162:163]
	v_pk_mul_f32 v[108:109], v[108:109], v[166:167]
	v_pk_mul_f32 v[116:117], v[110:111], v[164:165]
	v_pk_mul_f32 v[118:119], v[146:147], v[168:169]
	v_pk_fma_f32 v[106:107], v[132:133], v[106:107], v[140:141]
	v_pk_fma_f32 v[110:111], v[134:135], v[108:109], v[142:143]
	v_pk_fma_f32 v[108:109], v[136:137], v[116:117], v[144:145]
	v_pk_fma_f32 v[112:113], v[138:139], v[118:119], v[112:113]
	global_store_dwordx4 v[124:125], v[106:109], off
	global_store_dwordx4 v[124:125], v[110:113], off offset:16
	s_nop 0
	v_add_f32_e32 v66, 1.0, v66
	v_add_f32_e32 v71, 1.0, v71
	v_add_f32_e32 v67, 1.0, v67
	v_add_f32_e32 v72, 1.0, v72
	v_add_f32_e32 v73, 1.0, v73
	v_add_f32_e32 v68, 1.0, v68
	v_add_f32_e32 v69, 1.0, v69
	v_rcp_f32_e32 v116, v70
	v_rcp_f32_e32 v118, v66
	v_rcp_f32_e32 v117, v71
	v_rcp_f32_e32 v119, v67
	v_rcp_f32_e32 v126, v72
	v_rcp_f32_e32 v127, v73
	v_rcp_f32_e32 v128, v68
	v_rcp_f32_e32 v129, v69
	s_waitcnt vmcnt(15)
	v_lshlrev_b32_e32 v66, 16, v102
	v_and_b32_e32 v67, 0xffff0000, v102
	v_lshlrev_b32_e32 v68, 16, v104
	v_and_b32_e32 v69, 0xffff0000, v104
	v_lshlrev_b32_e32 v70, 16, v103
	v_and_b32_e32 v71, 0xffff0000, v103
	s_waitcnt vmcnt(14)
	v_lshlrev_b32_e32 v132, 16, v98
	v_and_b32_e32 v133, 0xffff0000, v98
	v_lshlrev_b32_e32 v134, 16, v100
	v_and_b32_e32 v135, 0xffff0000, v100
	v_lshlrev_b32_e32 v136, 16, v99
	v_and_b32_e32 v137, 0xffff0000, v99
	v_lshlrev_b32_e32 v72, 16, v105
	v_and_b32_e32 v73, 0xffff0000, v105
	v_lshlrev_b32_e32 v104, 16, v101
	v_and_b32_e32 v105, 0xffff0000, v101
	v_pk_mul_f32 v[98:99], v[188:189], v[66:67] op_sel_hi:[0,1]
	v_pk_mul_f32 v[100:101], v[188:189], v[68:69] op_sel_hi:[0,1]
	v_pk_mul_f32 v[102:103], v[188:189], v[70:71] op_sel_hi:[0,1]
	v_pk_mul_f32 v[138:139], v[188:189], v[72:73] op_sel_hi:[0,1]
	global_load_dwordx4 v[70:73], v[130:131], off offset:256 nt
	global_load_dwordx4 v[66:69], v[120:121], off offset:256
	v_lshlrev_b64 v[120:121], 12, v[122:123]
	v_lshl_add_u64 v[120:121], s[48:49], 0, v[120:121]
	v_lshl_add_u64 v[120:121], v[120:121], 0, v[180:181]
	v_pk_mul_f32 v[98:99], v[98:99], v[170:171]
	v_pk_mul_f32 v[100:101], v[100:101], v[174:175]
	v_pk_mul_f32 v[106:107], v[102:103], v[172:173]
	v_pk_mul_f32 v[108:109], v[138:139], v[176:177]
	v_pk_fma_f32 v[98:99], v[116:117], v[98:99], v[132:133]
	v_pk_fma_f32 v[102:103], v[118:119], v[100:101], v[134:135]
	v_pk_fma_f32 v[100:101], v[126:127], v[106:107], v[136:137]
	v_pk_fma_f32 v[104:105], v[128:129], v[108:109], v[104:105]
	global_store_dwordx4 v[124:125], v[98:101], off offset:512
	global_store_dwordx4 v[124:125], v[102:105], off offset:528
	s_nop 0
	ds_read_b32 v107, v203
	ds_read_b32 v106, v204
	ds_read_b32 v109, v205
	ds_read_b32 v110, v206
	ds_read_b32 v113, v207
	ds_read_b32 v112, v208
	ds_read_b32 v111, v209
	ds_read_b32 v108, v210
	s_waitcnt lgkmcnt(7)
	v_mul_f32_e32 v107, 0xbfb8aa3b, v107
	v_mul_f32_e32 v62, v62, v107
	v_mul_f32_e32 v58, v58, v107
	v_mul_f32_e32 v63, v63, v107
	v_mul_f32_e32 v59, v59, v107
	v_mul_f32_e32 v64, v64, v107
	v_mul_f32_e32 v65, v65, v107
	v_mul_f32_e32 v60, v60, v107
	v_mul_f32_e32 v61, v61, v107
	v_exp_f32_e32 v62, v62
	v_exp_f32_e32 v58, v58
	v_exp_f32_e32 v63, v63
	v_exp_f32_e32 v59, v59
	v_exp_f32_e32 v64, v64
	v_exp_f32_e32 v65, v65
	v_exp_f32_e32 v60, v60
	v_exp_f32_e32 v61, v61
	v_add_f32_e32 v62, 1.0, v62
	v_add_f32_e32 v58, 1.0, v58
	v_add_f32_e32 v63, 1.0, v63
	v_add_f32_e32 v59, 1.0, v59
	v_add_f32_e32 v64, 1.0, v64
	v_add_f32_e32 v65, 1.0, v65
	v_add_u32_e32 v116, 0xa0, v184
	v_add_f32_e32 v60, 1.0, v60
	v_add_f32_e32 v61, 1.0, v61
	v_rcp_f32_e32 v124, v62
	v_rcp_f32_e32 v126, v58
	v_rcp_f32_e32 v125, v63
	v_rcp_f32_e32 v127, v59
	v_rcp_f32_e32 v128, v64
	v_rcp_f32_e32 v129, v65
	v_ashrrev_i32_e32 v117, 31, v116
	v_rcp_f32_e32 v130, v60
	v_rcp_f32_e32 v131, v61
	s_waitcnt vmcnt(15)
	v_lshlrev_b32_e32 v58, 16, v94
	v_and_b32_e32 v59, 0xffff0000, v94
	v_lshlrev_b32_e32 v60, 16, v96
	v_and_b32_e32 v61, 0xffff0000, v96
	v_lshlrev_b32_e32 v62, 16, v95
	v_and_b32_e32 v63, 0xffff0000, v95
	v_lshlrev_b64 v[118:119], 11, v[116:117]
	s_waitcnt vmcnt(14)
	v_lshlrev_b32_e32 v132, 16, v90
	v_and_b32_e32 v133, 0xffff0000, v90
	v_lshlrev_b32_e32 v134, 16, v92
	v_and_b32_e32 v135, 0xffff0000, v92
	v_lshlrev_b32_e32 v136, 16, v91
	v_and_b32_e32 v137, 0xffff0000, v91
	v_lshlrev_b32_e32 v64, 16, v97
	v_and_b32_e32 v65, 0xffff0000, v97
	v_lshlrev_b32_e32 v96, 16, v93
	v_and_b32_e32 v97, 0xffff0000, v93
	s_waitcnt lgkmcnt(6)
	v_pk_mul_f32 v[90:91], v[106:107], v[58:59] op_sel_hi:[0,1]
	v_pk_mul_f32 v[92:93], v[106:107], v[60:61] op_sel_hi:[0,1]
	v_pk_mul_f32 v[94:95], v[106:107], v[62:63] op_sel_hi:[0,1]
	v_lshl_add_u64 v[122:123], s[82:83], 0, v[118:119]
	v_pk_mul_f32 v[138:139], v[106:107], v[64:65] op_sel_hi:[0,1]
	v_lshl_add_u64 v[118:119], s[18:19], 0, v[118:119]
	v_lshl_add_u64 v[122:123], v[122:123], 0, v[182:183]
	v_lshl_add_u64 v[118:119], v[118:119], 0, v[182:183]
	global_load_dwordx4 v[62:65], v[122:123], off nt
	global_load_dwordx4 v[58:61], v[118:119], off
	v_mul_f32_e32 v54, v54, v107
	v_mul_f32_e32 v50, v50, v107
	v_mul_f32_e32 v55, v55, v107
	v_mul_f32_e32 v51, v51, v107
	v_mul_f32_e32 v56, v56, v107
	v_mul_f32_e32 v57, v57, v107
	v_mul_f32_e32 v52, v52, v107
	v_mul_f32_e32 v53, v53, v107
	v_exp_f32_e32 v54, v54
	v_exp_f32_e32 v50, v50
	v_exp_f32_e32 v55, v55
	v_exp_f32_e32 v51, v51
	v_exp_f32_e32 v56, v56
	v_exp_f32_e32 v57, v57
	v_exp_f32_e32 v52, v52
	v_exp_f32_e32 v53, v53
	v_pk_mul_f32 v[90:91], v[90:91], v[162:163]
	v_pk_mul_f32 v[92:93], v[92:93], v[166:167]
	v_pk_mul_f32 v[98:99], v[94:95], v[164:165]
	v_pk_mul_f32 v[100:101], v[138:139], v[168:169]
	v_pk_fma_f32 v[90:91], v[124:125], v[90:91], v[132:133]
	v_pk_fma_f32 v[94:95], v[126:127], v[92:93], v[134:135]
	v_pk_fma_f32 v[92:93], v[128:129], v[98:99], v[136:137]
	v_pk_fma_f32 v[96:97], v[130:131], v[100:101], v[96:97]
	global_store_dwordx4 v[120:121], v[90:93], off
	global_store_dwordx4 v[120:121], v[94:97], off offset:16
	s_nop 0
	v_add_f32_e32 v54, 1.0, v54
	v_add_f32_e32 v50, 1.0, v50
	v_add_f32_e32 v55, 1.0, v55
	v_add_f32_e32 v51, 1.0, v51
	v_add_f32_e32 v56, 1.0, v56
	v_add_f32_e32 v57, 1.0, v57
	v_add_f32_e32 v52, 1.0, v52
	v_add_f32_e32 v53, 1.0, v53
	v_rcp_f32_e32 v98, v54
	v_rcp_f32_e32 v100, v50
	v_rcp_f32_e32 v99, v55
	v_rcp_f32_e32 v101, v51
	v_rcp_f32_e32 v102, v56
	v_rcp_f32_e32 v103, v57
	v_rcp_f32_e32 v104, v52
	v_rcp_f32_e32 v105, v53
	s_waitcnt vmcnt(15)
	v_lshlrev_b32_e32 v50, 16, v86
	v_and_b32_e32 v51, 0xffff0000, v86
	v_lshlrev_b32_e32 v52, 16, v88
	v_and_b32_e32 v53, 0xffff0000, v88
	v_lshlrev_b32_e32 v54, 16, v87
	v_and_b32_e32 v55, 0xffff0000, v87
	s_waitcnt vmcnt(14)
	v_lshlrev_b32_e32 v124, 16, v82
	v_and_b32_e32 v125, 0xffff0000, v82
	v_lshlrev_b32_e32 v126, 16, v84
	v_and_b32_e32 v127, 0xffff0000, v84
	v_lshlrev_b32_e32 v128, 16, v83
	v_and_b32_e32 v129, 0xffff0000, v83
	v_lshlrev_b32_e32 v56, 16, v89
	v_and_b32_e32 v57, 0xffff0000, v89
	v_lshlrev_b32_e32 v88, 16, v85
	v_and_b32_e32 v89, 0xffff0000, v85
	v_pk_mul_f32 v[82:83], v[106:107], v[50:51] op_sel_hi:[0,1]
	v_pk_mul_f32 v[84:85], v[106:107], v[52:53] op_sel_hi:[0,1]
	v_pk_mul_f32 v[86:87], v[106:107], v[54:55] op_sel_hi:[0,1]
	v_pk_mul_f32 v[106:107], v[106:107], v[56:57] op_sel_hi:[0,1]
	global_load_dwordx4 v[54:57], v[122:123], off offset:256 nt
	global_load_dwordx4 v[50:53], v[118:119], off offset:256
	s_waitcnt lgkmcnt(5)
	v_mul_f32_e32 v109, 0xbfb8aa3b, v109
	v_mul_f32_e32 v46, v46, v109
	v_mul_f32_e32 v42, v42, v109
	v_mul_f32_e32 v47, v47, v109
	v_mul_f32_e32 v43, v43, v109
	v_mul_f32_e32 v48, v48, v109
	v_mul_f32_e32 v49, v49, v109
	v_mul_f32_e32 v44, v44, v109
	v_mul_f32_e32 v45, v45, v109
	v_exp_f32_e32 v46, v46
	v_exp_f32_e32 v42, v42
	v_exp_f32_e32 v47, v47
	v_exp_f32_e32 v43, v43
	v_exp_f32_e32 v48, v48
	v_exp_f32_e32 v49, v49
	v_exp_f32_e32 v44, v44
	v_exp_f32_e32 v45, v45
	v_add_f32_e32 v46, 1.0, v46
	v_add_f32_e32 v42, 1.0, v42
	v_add_f32_e32 v47, 1.0, v47
	v_add_f32_e32 v43, 1.0, v43
	v_add_f32_e32 v48, 1.0, v48
	v_add_f32_e32 v49, 1.0, v49
	v_add_f32_e32 v44, 1.0, v44
	v_add_f32_e32 v45, 1.0, v45
	s_waitcnt vmcnt(12)
	v_lshlrev_b32_e32 v118, 16, v75
	v_and_b32_e32 v119, 0xffff0000, v75
	v_mul_f32_e32 v38, v38, v109
	v_mul_f32_e32 v34, v34, v109
	v_mul_f32_e32 v39, v39, v109
	v_mul_f32_e32 v35, v35, v109
	v_mul_f32_e32 v40, v40, v109
	v_mul_f32_e32 v41, v41, v109
	v_mul_f32_e32 v36, v36, v109
	v_mul_f32_e32 v37, v37, v109
	v_exp_f32_e32 v38, v38
	v_exp_f32_e32 v34, v34
	v_exp_f32_e32 v39, v39
	v_exp_f32_e32 v35, v35
	v_exp_f32_e32 v40, v40
	v_exp_f32_e32 v41, v41
	v_pk_mul_f32 v[82:83], v[82:83], v[170:171]
	v_pk_mul_f32 v[84:85], v[84:85], v[174:175]
	v_pk_mul_f32 v[90:91], v[86:87], v[172:173]
	v_pk_mul_f32 v[92:93], v[106:107], v[176:177]
	v_pk_fma_f32 v[82:83], v[98:99], v[82:83], v[124:125]
	v_pk_fma_f32 v[86:87], v[100:101], v[84:85], v[126:127]
	v_pk_fma_f32 v[84:85], v[102:103], v[90:91], v[128:129]
	v_pk_fma_f32 v[88:89], v[104:105], v[92:93], v[88:89]
	global_store_dwordx4 v[120:121], v[82:85], off offset:512
	global_store_dwordx4 v[120:121], v[86:89], off offset:528
	s_nop 0
	v_add_u32_e32 v82, 0xb0, v184
	v_rcp_f32_e32 v98, v46
	v_rcp_f32_e32 v100, v42
	v_rcp_f32_e32 v99, v47
	v_rcp_f32_e32 v101, v43
	v_rcp_f32_e32 v102, v48
	v_rcp_f32_e32 v103, v49
	v_ashrrev_i32_e32 v83, 31, v82
	v_rcp_f32_e32 v104, v44
	v_rcp_f32_e32 v105, v45
	v_lshlrev_b32_e32 v42, 16, v78
	v_and_b32_e32 v43, 0xffff0000, v78
	v_lshlrev_b32_e32 v44, 16, v80
	v_and_b32_e32 v45, 0xffff0000, v80
	v_lshlrev_b32_e32 v46, 16, v79
	v_and_b32_e32 v47, 0xffff0000, v79
	v_lshlrev_b64 v[92:93], 11, v[82:83]
	v_lshlrev_b64 v[94:95], 12, v[114:115]
	v_lshlrev_b32_e32 v106, 16, v74
	v_and_b32_e32 v107, 0xffff0000, v74
	v_lshlrev_b32_e32 v114, 16, v76
	v_and_b32_e32 v115, 0xffff0000, v76
	v_lshlrev_b32_e32 v48, 16, v81
	v_and_b32_e32 v49, 0xffff0000, v81
	v_lshlrev_b32_e32 v80, 16, v77
	v_and_b32_e32 v81, 0xffff0000, v77
	s_waitcnt lgkmcnt(1)
	v_pk_mul_f32 v[74:75], v[110:111], v[42:43] op_sel_hi:[0,1]
	v_pk_mul_f32 v[76:77], v[110:111], v[44:45] op_sel_hi:[0,1]
	v_pk_mul_f32 v[78:79], v[110:111], v[46:47] op_sel_hi:[0,1]
	v_lshl_add_u64 v[96:97], s[82:83], 0, v[92:93]
	v_lshl_add_u64 v[94:95], s[48:49], 0, v[94:95]
	v_pk_mul_f32 v[120:121], v[110:111], v[48:49] op_sel_hi:[0,1]
	v_lshl_add_u64 v[92:93], s[18:19], 0, v[92:93]
	v_lshl_add_u64 v[96:97], v[96:97], 0, v[182:183]
	v_lshl_add_u64 v[94:95], v[94:95], 0, v[180:181]
	v_lshl_add_u64 v[92:93], v[92:93], 0, v[182:183]
	global_load_dwordx4 v[46:49], v[96:97], off nt
	global_load_dwordx4 v[42:45], v[92:93], off
	v_exp_f32_e32 v36, v36
	v_exp_f32_e32 v37, v37
	v_add_f32_e32 v38, 1.0, v38
	v_add_f32_e32 v34, 1.0, v34
	v_add_f32_e32 v39, 1.0, v39
	v_add_f32_e32 v35, 1.0, v35
	v_add_f32_e32 v40, 1.0, v40
	v_add_f32_e32 v41, 1.0, v41
	v_add_f32_e32 v36, 1.0, v36
	v_add_f32_e32 v37, 1.0, v37
	v_pk_mul_f32 v[74:75], v[74:75], v[162:163]
	v_pk_mul_f32 v[76:77], v[76:77], v[166:167]
	v_pk_mul_f32 v[84:85], v[78:79], v[164:165]
	v_pk_mul_f32 v[86:87], v[120:121], v[168:169]
	v_pk_fma_f32 v[74:75], v[98:99], v[74:75], v[106:107]
	v_pk_fma_f32 v[78:79], v[100:101], v[76:77], v[114:115]
	v_pk_fma_f32 v[76:77], v[102:103], v[84:85], v[118:119]
	v_pk_fma_f32 v[80:81], v[104:105], v[86:87], v[80:81]
	global_store_dwordx4 v[94:95], v[74:77], off
	global_store_dwordx4 v[94:95], v[78:81], off offset:16
	s_nop 0
	v_rcp_f32_e32 v84, v38
	v_rcp_f32_e32 v86, v34
	v_rcp_f32_e32 v85, v39
	v_rcp_f32_e32 v87, v35
	v_rcp_f32_e32 v88, v40
	v_rcp_f32_e32 v89, v41
	v_rcp_f32_e32 v90, v36
	v_rcp_f32_e32 v91, v37
	s_waitcnt vmcnt(15)
	v_lshlrev_b32_e32 v34, 16, v70
	v_and_b32_e32 v35, 0xffff0000, v70
	v_lshlrev_b32_e32 v36, 16, v72
	v_and_b32_e32 v37, 0xffff0000, v72
	v_lshlrev_b32_e32 v38, 16, v71
	v_and_b32_e32 v39, 0xffff0000, v71
	s_waitcnt vmcnt(14)
	v_lshlrev_b32_e32 v98, 16, v66
	v_and_b32_e32 v99, 0xffff0000, v66
	v_lshlrev_b32_e32 v100, 16, v68
	v_and_b32_e32 v101, 0xffff0000, v68
	v_lshlrev_b32_e32 v102, 16, v67
	v_and_b32_e32 v103, 0xffff0000, v67
	v_lshlrev_b32_e32 v40, 16, v73
	v_and_b32_e32 v41, 0xffff0000, v73
	v_lshlrev_b32_e32 v72, 16, v69
	v_and_b32_e32 v73, 0xffff0000, v69
	v_pk_mul_f32 v[66:67], v[110:111], v[34:35] op_sel_hi:[0,1]
	v_pk_mul_f32 v[68:69], v[110:111], v[36:37] op_sel_hi:[0,1]
	v_pk_mul_f32 v[70:71], v[110:111], v[38:39] op_sel_hi:[0,1]
	v_pk_mul_f32 v[104:105], v[110:111], v[40:41] op_sel_hi:[0,1]
	global_load_dwordx4 v[38:41], v[96:97], off offset:256 nt
	global_load_dwordx4 v[34:37], v[92:93], off offset:256
	v_pk_mul_f32 v[66:67], v[66:67], v[170:171]
	v_pk_mul_f32 v[68:69], v[68:69], v[174:175]
	v_pk_mul_f32 v[74:75], v[70:71], v[172:173]
	v_pk_mul_f32 v[76:77], v[104:105], v[176:177]
	v_pk_fma_f32 v[66:67], v[84:85], v[66:67], v[98:99]
	v_pk_fma_f32 v[70:71], v[86:87], v[68:69], v[100:101]
	v_pk_fma_f32 v[68:69], v[88:89], v[74:75], v[102:103]
	v_pk_fma_f32 v[72:73], v[90:91], v[76:77], v[72:73]
	global_store_dwordx4 v[94:95], v[66:69], off offset:512
	global_store_dwordx4 v[94:95], v[70:73], off offset:528
	s_nop 0
	v_mul_f32_e32 v86, 0xbfb8aa3b, v113
	v_mul_f32_e32 v30, v30, v86
	v_mul_f32_e32 v26, v26, v86
	v_mul_f32_e32 v31, v31, v86
	v_mul_f32_e32 v27, v27, v86
	v_mul_f32_e32 v32, v32, v86
	v_mul_f32_e32 v33, v33, v86
	v_mul_f32_e32 v28, v28, v86
	v_mul_f32_e32 v29, v29, v86
	v_exp_f32_e32 v30, v30
	v_exp_f32_e32 v26, v26
	v_exp_f32_e32 v31, v31
	v_exp_f32_e32 v27, v27
	v_exp_f32_e32 v32, v32
	v_exp_f32_e32 v33, v33
	v_exp_f32_e32 v28, v28
	v_exp_f32_e32 v29, v29
	v_add_f32_e32 v30, 1.0, v30
	v_add_f32_e32 v76, 1.0, v26
	v_add_f32_e32 v31, 1.0, v31
	v_add_f32_e32 v77, 1.0, v27
	v_add_f32_e32 v32, 1.0, v32
	v_add_f32_e32 v33, 1.0, v33
	v_add_f32_e32 v78, 1.0, v28
	v_add_f32_e32 v79, 1.0, v29
	v_rcp_f32_e32 v26, v30
	v_rcp_f32_e32 v28, v76
	v_rcp_f32_e32 v27, v31
	v_rcp_f32_e32 v29, v77
	v_rcp_f32_e32 v32, v32
	v_rcp_f32_e32 v33, v33
	v_rcp_f32_e32 v76, v78
	v_rcp_f32_e32 v77, v79
	s_waitcnt vmcnt(15)
	v_lshlrev_b32_e32 v30, 16, v62
	v_and_b32_e32 v31, 0xffff0000, v62
	v_lshlrev_b32_e32 v80, 16, v64
	v_and_b32_e32 v81, 0xffff0000, v64
	v_lshlrev_b32_e32 v62, 16, v63
	v_and_b32_e32 v63, 0xffff0000, v63
	v_lshlrev_b64 v[74:75], 12, v[116:117]
	v_lshlrev_b32_e32 v64, 16, v65
	v_and_b32_e32 v65, 0xffff0000, v65
	v_pk_mul_f32 v[30:31], v[112:113], v[30:31] op_sel_hi:[0,1]
	v_pk_mul_f32 v[80:81], v[112:113], v[80:81] op_sel_hi:[0,1]
	v_pk_mul_f32 v[62:63], v[112:113], v[62:63] op_sel_hi:[0,1]
	v_lshl_add_u64 v[74:75], s[48:49], 0, v[74:75]
	s_waitcnt vmcnt(14)
	v_lshlrev_b32_e32 v78, 16, v58
	v_and_b32_e32 v79, 0xffff0000, v58
	v_lshlrev_b32_e32 v84, 16, v60
	v_and_b32_e32 v85, 0xffff0000, v60
	v_lshlrev_b32_e32 v58, 16, v59
	v_and_b32_e32 v59, 0xffff0000, v59
	v_pk_mul_f32 v[64:65], v[112:113], v[64:65] op_sel_hi:[0,1]
	v_lshl_add_u64 v[74:75], v[74:75], 0, v[180:181]
	v_lshlrev_b32_e32 v60, 16, v61
	v_and_b32_e32 v61, 0xffff0000, v61
	v_mul_f32_e32 v22, v22, v86
	v_mul_f32_e32 v18, v18, v86
	v_mul_f32_e32 v23, v23, v86
	v_mul_f32_e32 v19, v19, v86
	v_mul_f32_e32 v24, v24, v86
	v_mul_f32_e32 v25, v25, v86
	v_mul_f32_e32 v20, v20, v86
	v_mul_f32_e32 v21, v21, v86
	v_exp_f32_e32 v22, v22
	v_exp_f32_e32 v18, v18
	v_exp_f32_e32 v23, v23
	v_exp_f32_e32 v19, v19
	v_exp_f32_e32 v24, v24
	v_exp_f32_e32 v25, v25
	v_exp_f32_e32 v20, v20
	v_exp_f32_e32 v21, v21
	v_add_f32_e32 v22, 1.0, v22
	v_add_f32_e32 v23, 1.0, v23
	v_add_f32_e32 v24, 1.0, v24
	v_add_f32_e32 v25, 1.0, v25
	v_rcp_f32_e32 v24, v24
	v_rcp_f32_e32 v25, v25
	v_pk_mul_f32 v[30:31], v[30:31], v[162:163]
	v_pk_mul_f32 v[66:67], v[80:81], v[166:167]
	v_pk_mul_f32 v[62:63], v[62:63], v[164:165]
	v_pk_mul_f32 v[64:65], v[64:65], v[168:169]
	v_pk_fma_f32 v[26:27], v[30:31], v[26:27], v[78:79]
	v_pk_fma_f32 v[30:31], v[66:67], v[28:29], v[84:85]
	v_pk_fma_f32 v[28:29], v[62:63], v[32:33], v[58:59]
	v_pk_fma_f32 v[32:33], v[64:65], v[76:77], v[60:61]
	global_store_dwordx4 v[74:75], v[26:29], off
	global_store_dwordx4 v[74:75], v[30:33], off offset:16
	s_nop 0
	v_add_f32_e32 v58, 1.0, v18
	v_add_f32_e32 v59, 1.0, v19
	v_add_f32_e32 v60, 1.0, v20
	v_add_f32_e32 v61, 1.0, v21
	v_rcp_f32_e32 v18, v22
	v_rcp_f32_e32 v20, v58
	v_rcp_f32_e32 v19, v23
	v_rcp_f32_e32 v21, v59
	v_rcp_f32_e32 v58, v60
	v_rcp_f32_e32 v59, v61
	s_waitcnt vmcnt(13)
	v_lshlrev_b32_e32 v22, 16, v54
	v_and_b32_e32 v23, 0xffff0000, v54
	v_lshlrev_b32_e32 v62, 16, v56
	v_and_b32_e32 v63, 0xffff0000, v56
	v_lshlrev_b32_e32 v54, 16, v55
	v_and_b32_e32 v55, 0xffff0000, v55
	v_lshlrev_b32_e32 v56, 16, v57
	v_and_b32_e32 v57, 0xffff0000, v57
	v_pk_mul_f32 v[22:23], v[112:113], v[22:23] op_sel_hi:[0,1]
	v_pk_mul_f32 v[62:63], v[112:113], v[62:63] op_sel_hi:[0,1]
	v_pk_mul_f32 v[54:55], v[112:113], v[54:55] op_sel_hi:[0,1]
	s_waitcnt vmcnt(12)
	v_lshlrev_b32_e32 v60, 16, v50
	v_and_b32_e32 v61, 0xffff0000, v50
	v_lshlrev_b32_e32 v64, 16, v52
	v_and_b32_e32 v65, 0xffff0000, v52
	v_lshlrev_b32_e32 v50, 16, v51
	v_and_b32_e32 v51, 0xffff0000, v51
	v_pk_mul_f32 v[56:57], v[112:113], v[56:57] op_sel_hi:[0,1]
	v_lshlrev_b32_e32 v52, 16, v53
	v_and_b32_e32 v53, 0xffff0000, v53
	v_pk_mul_f32 v[22:23], v[22:23], v[170:171]
	v_pk_mul_f32 v[26:27], v[62:63], v[174:175]
	v_pk_mul_f32 v[28:29], v[54:55], v[172:173]
	v_pk_mul_f32 v[30:31], v[56:57], v[176:177]
	v_pk_fma_f32 v[18:19], v[18:19], v[22:23], v[60:61]
	v_pk_fma_f32 v[22:23], v[20:21], v[26:27], v[64:65]
	v_pk_fma_f32 v[20:21], v[24:25], v[28:29], v[50:51]
	v_pk_fma_f32 v[24:25], v[58:59], v[30:31], v[52:53]
	global_store_dwordx4 v[74:75], v[18:21], off offset:512
	global_store_dwordx4 v[74:75], v[22:25], off offset:528
	s_nop 0
	v_mul_f32_e32 v52, 0xbfb8aa3b, v111
	v_mul_f32_e32 v14, v14, v52
	v_mul_f32_e32 v10, v10, v52
	v_mul_f32_e32 v15, v15, v52
	v_mul_f32_e32 v11, v11, v52
	v_mul_f32_e32 v16, v16, v52
	v_mul_f32_e32 v17, v17, v52
	v_mul_f32_e32 v12, v12, v52
	v_mul_f32_e32 v13, v13, v52
	v_exp_f32_e32 v14, v14
	v_exp_f32_e32 v10, v10
	v_exp_f32_e32 v15, v15
	v_exp_f32_e32 v11, v11
	v_exp_f32_e32 v16, v16
	v_exp_f32_e32 v17, v17
	v_exp_f32_e32 v12, v12
	v_exp_f32_e32 v13, v13
	v_add_f32_e32 v14, 1.0, v14
	v_add_f32_e32 v28, 1.0, v10
	v_add_f32_e32 v15, 1.0, v15
	v_add_f32_e32 v29, 1.0, v11
	v_add_f32_e32 v16, 1.0, v16
	v_add_f32_e32 v17, 1.0, v17
	v_add_f32_e32 v30, 1.0, v12
	v_add_f32_e32 v31, 1.0, v13
	v_rcp_f32_e32 v10, v14
	v_rcp_f32_e32 v12, v28
	v_rcp_f32_e32 v11, v15
	v_rcp_f32_e32 v13, v29
	v_rcp_f32_e32 v16, v16
	v_rcp_f32_e32 v17, v17
	v_rcp_f32_e32 v28, v30
	v_rcp_f32_e32 v29, v31
	s_waitcnt vmcnt(11)
	v_lshlrev_b32_e32 v14, 16, v46
	v_and_b32_e32 v15, 0xffff0000, v46
	v_lshlrev_b32_e32 v32, 16, v48
	v_and_b32_e32 v33, 0xffff0000, v48
	v_lshlrev_b32_e32 v46, 16, v47
	v_and_b32_e32 v47, 0xffff0000, v47
	v_lshlrev_b64 v[26:27], 12, v[82:83]
	v_lshlrev_b32_e32 v48, 16, v49
	v_and_b32_e32 v49, 0xffff0000, v49
	s_waitcnt lgkmcnt(0)
	v_pk_mul_f32 v[14:15], v[108:109], v[14:15] op_sel_hi:[0,1]
	v_pk_mul_f32 v[32:33], v[108:109], v[32:33] op_sel_hi:[0,1]
	v_pk_mul_f32 v[46:47], v[108:109], v[46:47] op_sel_hi:[0,1]
	v_lshl_add_u64 v[26:27], s[48:49], 0, v[26:27]
	s_waitcnt vmcnt(10)
	v_lshlrev_b32_e32 v30, 16, v42
	v_and_b32_e32 v31, 0xffff0000, v42
	v_lshlrev_b32_e32 v50, 16, v44
	v_and_b32_e32 v51, 0xffff0000, v44
	v_lshlrev_b32_e32 v42, 16, v43
	v_and_b32_e32 v43, 0xffff0000, v43
	v_pk_mul_f32 v[48:49], v[108:109], v[48:49] op_sel_hi:[0,1]
	v_lshl_add_u64 v[26:27], v[26:27], 0, v[180:181]
	v_lshlrev_b32_e32 v44, 16, v45
	v_and_b32_e32 v45, 0xffff0000, v45
	v_mul_f32_e32 v6, v6, v52
	v_mul_f32_e32 v2, v2, v52
	v_mul_f32_e32 v7, v7, v52
	v_mul_f32_e32 v3, v3, v52
	v_mul_f32_e32 v8, v8, v52
	v_mul_f32_e32 v9, v9, v52
	v_mul_f32_e32 v4, v4, v52
	v_mul_f32_e32 v5, v5, v52
	v_exp_f32_e32 v6, v6
	v_exp_f32_e32 v2, v2
	v_exp_f32_e32 v7, v7
	v_exp_f32_e32 v3, v3
	v_exp_f32_e32 v8, v8
	v_exp_f32_e32 v9, v9
	v_exp_f32_e32 v4, v4
	v_exp_f32_e32 v5, v5
	v_add_f32_e32 v6, 1.0, v6
	v_add_f32_e32 v7, 1.0, v7
	v_add_f32_e32 v8, 1.0, v8
	v_add_f32_e32 v9, 1.0, v9
	v_rcp_f32_e32 v8, v8
	v_rcp_f32_e32 v9, v9
	v_pk_mul_f32 v[14:15], v[14:15], v[162:163]
	v_pk_mul_f32 v[18:19], v[32:33], v[166:167]
	v_pk_mul_f32 v[20:21], v[46:47], v[164:165]
	v_pk_mul_f32 v[22:23], v[48:49], v[168:169]
	v_pk_fma_f32 v[10:11], v[14:15], v[10:11], v[30:31]
	v_pk_fma_f32 v[14:15], v[18:19], v[12:13], v[50:51]
	v_pk_fma_f32 v[12:13], v[20:21], v[16:17], v[42:43]
	v_pk_fma_f32 v[16:17], v[22:23], v[28:29], v[44:45]
	global_store_dwordx4 v[26:27], v[10:13], off
	global_store_dwordx4 v[26:27], v[14:17], off offset:16
	s_nop 0
	v_add_f32_e32 v18, 1.0, v2
	v_add_f32_e32 v19, 1.0, v3
	v_add_f32_e32 v20, 1.0, v4
	v_add_f32_e32 v21, 1.0, v5
	v_rcp_f32_e32 v2, v6
	v_rcp_f32_e32 v4, v18
	v_rcp_f32_e32 v3, v7
	v_rcp_f32_e32 v5, v19
	v_rcp_f32_e32 v18, v20
	v_rcp_f32_e32 v19, v21
	s_waitcnt vmcnt(9)
	v_lshlrev_b32_e32 v6, 16, v38
	v_and_b32_e32 v7, 0xffff0000, v38
	v_lshlrev_b32_e32 v22, 16, v40
	v_and_b32_e32 v23, 0xffff0000, v40
	v_lshlrev_b32_e32 v28, 16, v39
	v_and_b32_e32 v29, 0xffff0000, v39
	v_lshlrev_b32_e32 v32, 16, v41
	v_and_b32_e32 v33, 0xffff0000, v41
	v_pk_mul_f32 v[6:7], v[108:109], v[6:7] op_sel_hi:[0,1]
	v_pk_mul_f32 v[22:23], v[108:109], v[22:23] op_sel_hi:[0,1]
	v_pk_mul_f32 v[28:29], v[108:109], v[28:29] op_sel_hi:[0,1]
	s_waitcnt vmcnt(8)
	v_lshlrev_b32_e32 v20, 16, v34
	v_and_b32_e32 v21, 0xffff0000, v34
	v_lshlrev_b32_e32 v24, 16, v36
	v_and_b32_e32 v25, 0xffff0000, v36
	v_lshlrev_b32_e32 v30, 16, v35
	v_and_b32_e32 v31, 0xffff0000, v35
	v_pk_mul_f32 v[32:33], v[108:109], v[32:33] op_sel_hi:[0,1]
	v_lshlrev_b32_e32 v34, 16, v37
	v_and_b32_e32 v35, 0xffff0000, v37
	v_pk_mul_f32 v[6:7], v[6:7], v[170:171]
	v_pk_mul_f32 v[10:11], v[22:23], v[174:175]
	v_pk_mul_f32 v[12:13], v[28:29], v[172:173]
	v_pk_mul_f32 v[14:15], v[32:33], v[176:177]
	v_pk_fma_f32 v[2:3], v[2:3], v[6:7], v[20:21]
	v_pk_fma_f32 v[6:7], v[4:5], v[10:11], v[24:25]
	v_pk_fma_f32 v[4:5], v[8:9], v[12:13], v[30:31]
	v_pk_fma_f32 v[8:9], v[18:19], v[14:15], v[34:35]
	global_store_dwordx4 v[26:27], v[2:5], off offset:512
	global_store_dwordx4 v[26:27], v[6:9], off offset:528
	s_cbranch_vccz .LBB0_755
	s_waitcnt vmcnt(0)
	s_cmpk_gt_u32 s36, 0xff
	s_cbranch_scc1 .LBB0_766
	s_barrier
